# P1 h tile stores write-back (no nontemporal hint): dirty lines drain during the next K-loop instead of one burst
# baseline (speedup 1.0000x reference)
.LBB0_180:
	s_cmp_lt_i32 s99, 2
	s_cselect_b64 vcc, -1, 0
	v_lshl_or_b32 v150, s99, 8, v157
	v_cndmask_b32_e32 v148, 1.0, v162, vcc
	s_cmp_eq_u32 s99, 9
	v_mov_b64_e32 v[152:153], s[16:17]
	s_cselect_b64 s[10:11], -1, 0
	v_ashrrev_i32_e32 v151, 31, v150
	v_mad_i64_i32 v[152:153], s[12:13], v163, s92, v[152:153]
	s_waitcnt lgkmcnt(0)
	v_pk_mul_f32 v[120:121], v[148:149], v[120:121] op_sel_hi:[0,1]
	v_lshl_add_u64 v[152:153], v[150:151], 1, v[152:153]
	v_pk_mul_f32 v[122:123], v[148:149], v[122:123] op_sel_hi:[0,1]
	v_cvt_pk_bf16_f32 v120, v120, v121
	s_and_b64 s[12:13], s[68:69], s[10:11]
	v_pk_mul_f32 v[126:127], v[148:149], v[126:127] op_sel_hi:[0,1]
	v_pk_mul_f32 v[124:125], v[148:149], v[124:125] op_sel_hi:[0,1]
	v_cvt_pk_bf16_f32 v121, v122, v123
	v_cvt_pk_bf16_f32 v122, v124, v125
	v_cvt_pk_bf16_f32 v123, v126, v127
	global_store_dwordx4 v[152:153], v[120:123], off
	v_pk_mul_f32 v[118:119], v[148:149], v[118:119] op_sel_hi:[0,1]
	v_pk_mul_f32 v[116:117], v[148:149], v[116:117] op_sel_hi:[0,1]
	v_cndmask_b32_e64 v120, 0, 1, s[12:13]
	v_pk_mul_f32 v[114:115], v[148:149], v[114:115] op_sel_hi:[0,1]
	v_cmp_ne_u32_e64 s[10:11], 1, v120
	s_andn2_b64 vcc, exec, s[12:13]
	v_pk_mul_f32 v[112:113], v[148:149], v[112:113] op_sel_hi:[0,1]
	s_cbranch_vccnz .LBB0_182
	v_lshlrev_b32_e32 v120, 4, v163
	v_and_or_b32 v120, v120, s93, v156
	v_lshlrev_b32_e32 v149, 2, v120
	global_load_dwordx4 v[120:123], v149, s[46:47]
	global_load_dwordx4 v[124:127], v149, s[46:47] offset:16
	global_load_dwordx4 v[164:167], v149, s[44:45]
	global_load_dwordx4 v[168:171], v149, s[44:45] offset:16
	v_and_b32_e32 v172, 64, v161
	v_xor_b32_e32 v149, 32, v161
	v_add_u32_e32 v172, 64, v172
	v_cmp_lt_i32_e32 vcc, v149, v172
	s_nop 1
	v_cndmask_b32_e32 v149, v161, v149, vcc
	v_lshlrev_b32_e32 v149, 2, v149
	ds_bpermute_b32 v172, v149, v116
	ds_bpermute_b32 v173, v149, v117
	ds_bpermute_b32 v174, v149, v118
	ds_bpermute_b32 v175, v149, v119
	ds_bpermute_b32 v176, v149, v112
	ds_bpermute_b32 v178, v149, v114
	ds_bpermute_b32 v179, v149, v115
	ds_bpermute_b32 v177, v149, v113
	s_waitcnt vmcnt(0) lgkmcnt(0)
	v_pk_mul_f32 v[122:123], v[122:123], v[174:175]
	v_pk_mul_f32 v[120:121], v[120:121], v[172:173]
	v_pk_mul_f32 v[126:127], v[126:127], v[178:179]
	v_pk_mul_f32 v[124:125], v[124:125], v[176:177]
	v_pk_mul_f32 v[120:121], v[136:137], v[120:121]
	v_pk_mul_f32 v[122:123], v[138:139], v[122:123]
	v_pk_mul_f32 v[124:125], v[136:137], v[124:125]
	v_pk_mul_f32 v[126:127], v[138:139], v[126:127]
	v_pk_fma_f32 v[118:119], v[118:119], v[166:167], v[122:123]
	v_pk_fma_f32 v[116:117], v[116:117], v[164:165], v[120:121]
	v_pk_fma_f32 v[114:115], v[114:115], v[170:171], v[126:127]
	v_pk_fma_f32 v[112:113], v[112:113], v[168:169], v[124:125]
.LBB0_182:
	v_cvt_pk_bf16_f32 v116, v116, v117
	v_cvt_pk_bf16_f32 v117, v118, v119
	s_nop 0
	v_cvt_pk_bf16_f32 v118, v112, v113
	v_cvt_pk_bf16_f32 v119, v114, v115
	global_store_dwordx4 v[152:153], v[116:119], off offset:256
	v_cndmask_b32_e64 v112, 0, 1, s[74:75]
	v_cmp_ne_u32_e64 s[12:13], 1, v112
	s_andn2_b64 vcc, exec, s[74:75]
	v_or_b32_e32 v114, 16, v163
	s_cbranch_vccnz .LBB0_186
	v_mul_f32_e32 v112, v105, v105
	v_mul_f32_e32 v113, v107, v107
	v_fmac_f32_e32 v112, v104, v104
	v_fmac_f32_e32 v113, v106, v106
	v_add_f32_e32 v112, v112, v113
	v_mul_f32_e32 v113, v101, v101
	v_mul_f32_e32 v115, v103, v103
	v_fmac_f32_e32 v113, v100, v100
	v_fmac_f32_e32 v115, v102, v102
	v_add_f32_e32 v113, v113, v115
	v_mul_f32_e32 v115, v109, v109
	v_mul_f32_e32 v116, v111, v111
	v_fmac_f32_e32 v115, v108, v108
	v_fmac_f32_e32 v116, v110, v110
	v_add_f32_e32 v115, v115, v116
	v_add_f32_e32 v112, v115, v112
	v_mul_f32_e32 v115, v97, v97
	v_mul_f32_e32 v116, v99, v99
	v_fmac_f32_e32 v115, v96, v96
	v_fmac_f32_e32 v116, v98, v98
	v_add_f32_e32 v115, v115, v116
	v_add_f32_e32 v113, v115, v113
	v_add_f32_e32 v113, v113, v112
	v_and_b32_e32 v115, 64, v161
	v_cndmask_b32_e64 v112, v112, v113, s[8:9]
	v_xor_b32_e32 v113, 16, v161
	v_add_u32_e32 v115, 64, v115
	v_cmp_lt_i32_e32 vcc, v113, v115
	s_nop 1
	v_cndmask_b32_e32 v113, v161, v113, vcc
	v_lshlrev_b32_e32 v113, 2, v113
	ds_bpermute_b32 v113, v113, v112
	s_waitcnt lgkmcnt(0)
	v_add_f32_e32 v112, v112, v113
	v_xor_b32_e32 v113, 32, v161
	v_cmp_lt_i32_e32 vcc, v113, v115
	s_nop 1
	v_cndmask_b32_e32 v113, v161, v113, vcc
	v_lshlrev_b32_e32 v113, 2, v113
	ds_bpermute_b32 v113, v113, v112
	s_and_saveexec_b64 s[74:75], s[0:1]
	s_cbranch_execz .LBB0_185
	s_and_b64 s[98:99], s[8:9], exec
	s_cselect_b32 s98, s43, s41
	s_cselect_b32 s99, s42, s40
	v_lshl_or_b32 v118, v114, 2, s86
	v_mov_b32_e32 v116, s99
	v_mov_b32_e32 v117, s98
	v_ashrrev_i32_e32 v119, 31, v118
	v_lshl_add_u64 v[116:117], v[118:119], 2, v[116:117]
	s_waitcnt lgkmcnt(0)
	v_add_f32_e32 v112, v112, v113
	global_store_dword v[116:117], v112, off

.LBB0_186:
	s_waitcnt lgkmcnt(0)
	v_mov_b64_e32 v[112:113], s[16:17]
	v_mov_b32_e32 v149, v148
	v_mad_i64_i32 v[112:113], s[74:75], v114, s92, v[112:113]
	v_mov_b32_e32 v116, v148
	v_mov_b32_e32 v117, v148
	v_lshl_add_u64 v[112:113], v[150:151], 1, v[112:113]
	v_pk_mul_f32 v[106:107], v[116:117], v[106:107]
	v_pk_mul_f32 v[104:105], v[148:149], v[104:105]
	v_pk_mul_f32 v[102:103], v[116:117], v[102:103]
	v_pk_mul_f32 v[100:101], v[148:149], v[100:101]
	v_pk_mul_f32 v[98:99], v[116:117], v[98:99]
	s_and_b64 vcc, exec, s[10:11]
	v_pk_mul_f32 v[96:97], v[148:149], v[96:97]
	v_pk_mul_f32 v[110:111], v[116:117], v[110:111]
	v_pk_mul_f32 v[108:109], v[148:149], v[108:109]
	v_cvt_pk_bf16_f32 v104, v104, v105
	v_cvt_pk_bf16_f32 v105, v106, v107
	s_nop 0
	v_cvt_pk_bf16_f32 v106, v108, v109
	v_cvt_pk_bf16_f32 v107, v110, v111
	global_store_dwordx4 v[112:113], v[104:107], off
	s_cbranch_vccnz .LBB0_188
	s_nop 0
	v_lshlrev_b32_e32 v104, 4, v114
	v_and_or_b32 v104, v104, s94, v156
	v_lshlrev_b32_e32 v118, 2, v104
	global_load_dwordx4 v[104:107], v118, s[46:47]
	global_load_dwordx4 v[108:111], v118, s[46:47] offset:16
	global_load_dwordx4 v[114:117], v118, s[44:45]
	s_nop 0
	global_load_dwordx4 v[118:121], v118, s[44:45] offset:16
	v_and_b32_e32 v123, 64, v161
	v_xor_b32_e32 v122, 32, v161
	v_add_u32_e32 v123, 64, v123
	v_cmp_lt_i32_e32 vcc, v122, v123
	s_nop 1
	v_cndmask_b32_e32 v122, v161, v122, vcc
	v_lshlrev_b32_e32 v127, 2, v122
	ds_bpermute_b32 v122, v127, v100
	ds_bpermute_b32 v123, v127, v101
	ds_bpermute_b32 v124, v127, v102
	ds_bpermute_b32 v125, v127, v103
	ds_bpermute_b32 v126, v127, v96
	ds_bpermute_b32 v152, v127, v98
	ds_bpermute_b32 v153, v127, v99
	ds_bpermute_b32 v127, v127, v97
	s_waitcnt vmcnt(0) lgkmcnt(0)
	v_pk_mul_f32 v[106:107], v[106:107], v[124:125]
	v_pk_mul_f32 v[104:105], v[104:105], v[122:123]
	v_pk_mul_f32 v[110:111], v[110:111], v[152:153]
	v_pk_mul_f32 v[108:109], v[108:109], v[126:127]
	v_pk_mul_f32 v[104:105], v[136:137], v[104:105]
	v_pk_mul_f32 v[106:107], v[138:139], v[106:107]
	v_pk_mul_f32 v[108:109], v[136:137], v[108:109]
	v_pk_mul_f32 v[110:111], v[138:139], v[110:111]
	v_pk_fma_f32 v[102:103], v[102:103], v[116:117], v[106:107]
	v_pk_fma_f32 v[100:101], v[100:101], v[114:115], v[104:105]
	v_pk_fma_f32 v[98:99], v[98:99], v[120:121], v[110:111]
	v_pk_fma_f32 v[96:97], v[96:97], v[118:119], v[108:109]
.LBB0_188:
	v_cvt_pk_bf16_f32 v100, v100, v101
	v_cvt_pk_bf16_f32 v101, v102, v103
	s_nop 0
	v_cvt_pk_bf16_f32 v102, v96, v97
	v_cvt_pk_bf16_f32 v103, v98, v99
	global_store_dwordx4 v[112:113], v[100:103], off offset:256
	s_and_b64 vcc, exec, s[12:13]
	v_or_b32_e32 v98, 32, v163
	s_cbranch_vccnz .LBB0_192
	v_mul_f32_e32 v96, v89, v89
	v_mul_f32_e32 v97, v91, v91
	v_fmac_f32_e32 v96, v88, v88
	v_fmac_f32_e32 v97, v90, v90
	v_add_f32_e32 v96, v96, v97
	v_mul_f32_e32 v97, v85, v85
	v_mul_f32_e32 v99, v87, v87
	v_fmac_f32_e32 v97, v84, v84
	v_fmac_f32_e32 v99, v86, v86
	v_add_f32_e32 v97, v97, v99
	v_mul_f32_e32 v99, v93, v93
	v_mul_f32_e32 v100, v95, v95
	v_fmac_f32_e32 v99, v92, v92
	v_fmac_f32_e32 v100, v94, v94
	v_add_f32_e32 v99, v99, v100
	v_add_f32_e32 v96, v99, v96
	v_mul_f32_e32 v99, v81, v81
	v_mul_f32_e32 v100, v83, v83
	v_fmac_f32_e32 v99, v80, v80
	v_fmac_f32_e32 v100, v82, v82
	v_add_f32_e32 v99, v99, v100
	v_add_f32_e32 v97, v99, v97
	v_add_f32_e32 v97, v97, v96
	v_and_b32_e32 v99, 64, v161
	v_cndmask_b32_e64 v96, v96, v97, s[8:9]
	v_xor_b32_e32 v97, 16, v161
	v_add_u32_e32 v99, 64, v99
	v_cmp_lt_i32_e32 vcc, v97, v99
	s_nop 1
	v_cndmask_b32_e32 v97, v161, v97, vcc
	v_lshlrev_b32_e32 v97, 2, v97
	ds_bpermute_b32 v97, v97, v96
	s_waitcnt lgkmcnt(0)
	v_add_f32_e32 v96, v96, v97
	v_xor_b32_e32 v97, 32, v161
	v_cmp_lt_i32_e32 vcc, v97, v99
	s_nop 1
	v_cndmask_b32_e32 v97, v161, v97, vcc
	v_lshlrev_b32_e32 v97, 2, v97
	ds_bpermute_b32 v97, v97, v96
	s_and_saveexec_b64 s[74:75], s[0:1]
	s_cbranch_execz .LBB0_191
	s_and_b64 s[98:99], s[8:9], exec
	s_cselect_b32 s98, s43, s41
	s_cselect_b32 s99, s42, s40
	v_lshl_or_b32 v102, v98, 2, s86
	v_mov_b32_e32 v100, s99
	v_mov_b32_e32 v101, s98
	v_ashrrev_i32_e32 v103, 31, v102
	v_lshl_add_u64 v[100:101], v[102:103], 2, v[100:101]
	s_waitcnt lgkmcnt(0)
	v_add_f32_e32 v96, v96, v97
	global_store_dword v[100:101], v96, off

.LBB0_192:
	s_waitcnt lgkmcnt(0)
	v_mov_b64_e32 v[96:97], s[16:17]
	v_mad_i64_i32 v[96:97], s[74:75], v98, s92, v[96:97]
	v_mov_b32_e32 v100, v148
	v_mov_b32_e32 v101, v148
	v_lshl_add_u64 v[96:97], v[150:151], 1, v[96:97]
	v_pk_mul_f32 v[90:91], v[100:101], v[90:91]
	v_pk_mul_f32 v[88:89], v[148:149], v[88:89]
	v_pk_mul_f32 v[86:87], v[100:101], v[86:87]
	v_pk_mul_f32 v[84:85], v[148:149], v[84:85]
	v_pk_mul_f32 v[82:83], v[100:101], v[82:83]
	s_and_b64 vcc, exec, s[10:11]
	v_pk_mul_f32 v[80:81], v[148:149], v[80:81]
	v_pk_mul_f32 v[94:95], v[100:101], v[94:95]
	v_pk_mul_f32 v[92:93], v[148:149], v[92:93]
	v_cvt_pk_bf16_f32 v88, v88, v89
	v_cvt_pk_bf16_f32 v89, v90, v91
	s_nop 0
	v_cvt_pk_bf16_f32 v90, v92, v93
	v_cvt_pk_bf16_f32 v91, v94, v95
	global_store_dwordx4 v[96:97], v[88:91], off
	s_cbranch_vccnz .LBB0_194
	s_nop 0
	v_lshlrev_b32_e32 v88, 4, v98
	v_and_or_b32 v88, v88, s95, v156
	v_lshlrev_b32_e32 v102, 2, v88
	global_load_dwordx4 v[88:91], v102, s[46:47]
	global_load_dwordx4 v[92:95], v102, s[46:47] offset:16
	global_load_dwordx4 v[98:101], v102, s[44:45]
	s_nop 0
	global_load_dwordx4 v[102:105], v102, s[44:45] offset:16
	v_and_b32_e32 v107, 64, v161
	v_xor_b32_e32 v106, 32, v161
	v_add_u32_e32 v107, 64, v107
	v_cmp_lt_i32_e32 vcc, v106, v107
	s_nop 1
	v_cndmask_b32_e32 v106, v161, v106, vcc
	v_lshlrev_b32_e32 v111, 2, v106
	ds_bpermute_b32 v106, v111, v84
	ds_bpermute_b32 v107, v111, v85
	ds_bpermute_b32 v108, v111, v86
	ds_bpermute_b32 v109, v111, v87
	ds_bpermute_b32 v110, v111, v80
	ds_bpermute_b32 v112, v111, v82
	ds_bpermute_b32 v113, v111, v83
	ds_bpermute_b32 v111, v111, v81
	s_waitcnt vmcnt(0) lgkmcnt(0)
	v_pk_mul_f32 v[90:91], v[90:91], v[108:109]
	v_pk_mul_f32 v[88:89], v[88:89], v[106:107]
	v_pk_mul_f32 v[94:95], v[94:95], v[112:113]
	v_pk_mul_f32 v[92:93], v[92:93], v[110:111]
	v_pk_mul_f32 v[88:89], v[136:137], v[88:89]
	v_pk_mul_f32 v[90:91], v[138:139], v[90:91]
	v_pk_mul_f32 v[92:93], v[136:137], v[92:93]
	v_pk_mul_f32 v[94:95], v[138:139], v[94:95]
	v_pk_fma_f32 v[86:87], v[86:87], v[100:101], v[90:91]
	v_pk_fma_f32 v[84:85], v[84:85], v[98:99], v[88:89]
	v_pk_fma_f32 v[82:83], v[82:83], v[104:105], v[94:95]
	v_pk_fma_f32 v[80:81], v[80:81], v[102:103], v[92:93]
.LBB0_194:
	v_cvt_pk_bf16_f32 v84, v84, v85
	v_cvt_pk_bf16_f32 v85, v86, v87
	s_nop 0
	v_cvt_pk_bf16_f32 v86, v80, v81
	v_cvt_pk_bf16_f32 v87, v82, v83
	global_store_dwordx4 v[96:97], v[84:87], off offset:256
	s_and_b64 vcc, exec, s[12:13]
	v_or_b32_e32 v82, 48, v163
	s_cbranch_vccnz .LBB0_198
	v_mul_f32_e32 v80, v73, v73
	v_mul_f32_e32 v81, v75, v75
	v_fmac_f32_e32 v80, v72, v72
	v_fmac_f32_e32 v81, v74, v74
	v_add_f32_e32 v80, v80, v81
	v_mul_f32_e32 v81, v69, v69
	v_mul_f32_e32 v83, v71, v71
	v_fmac_f32_e32 v81, v68, v68
	v_fmac_f32_e32 v83, v70, v70
	v_add_f32_e32 v81, v81, v83
	v_mul_f32_e32 v83, v77, v77
	v_mul_f32_e32 v84, v79, v79
	v_fmac_f32_e32 v83, v76, v76
	v_fmac_f32_e32 v84, v78, v78
	v_add_f32_e32 v83, v83, v84
	v_add_f32_e32 v80, v83, v80
	v_mul_f32_e32 v83, v65, v65
	v_mul_f32_e32 v84, v67, v67
	v_fmac_f32_e32 v83, v64, v64
	v_fmac_f32_e32 v84, v66, v66
	v_add_f32_e32 v83, v83, v84
	v_add_f32_e32 v81, v83, v81
	v_add_f32_e32 v81, v81, v80
	v_and_b32_e32 v83, 64, v161
	v_cndmask_b32_e64 v80, v80, v81, s[8:9]
	v_xor_b32_e32 v81, 16, v161
	v_add_u32_e32 v83, 64, v83
	v_cmp_lt_i32_e32 vcc, v81, v83
	s_nop 1
	v_cndmask_b32_e32 v81, v161, v81, vcc
	v_lshlrev_b32_e32 v81, 2, v81
	ds_bpermute_b32 v81, v81, v80
	s_waitcnt lgkmcnt(0)
	v_add_f32_e32 v80, v80, v81
	v_xor_b32_e32 v81, 32, v161
	v_cmp_lt_i32_e32 vcc, v81, v83
	s_nop 1
	v_cndmask_b32_e32 v81, v161, v81, vcc
	v_lshlrev_b32_e32 v81, 2, v81
	ds_bpermute_b32 v81, v81, v80
	s_and_saveexec_b64 s[74:75], s[0:1]
	s_cbranch_execz .LBB0_197
	s_and_b64 s[98:99], s[8:9], exec
	s_cselect_b32 s98, s43, s41
	s_cselect_b32 s99, s42, s40
	v_lshl_or_b32 v86, v82, 2, s86
	v_mov_b32_e32 v84, s99
	v_mov_b32_e32 v85, s98
	v_ashrrev_i32_e32 v87, 31, v86
	v_lshl_add_u64 v[84:85], v[86:87], 2, v[84:85]
	s_waitcnt lgkmcnt(0)
	v_add_f32_e32 v80, v80, v81
	global_store_dword v[84:85], v80, off

.LBB0_198:
	s_waitcnt lgkmcnt(0)
	v_mov_b64_e32 v[80:81], s[16:17]
	v_mad_i64_i32 v[80:81], s[74:75], v82, s92, v[80:81]
	v_mov_b32_e32 v84, v148
	v_mov_b32_e32 v85, v148
	v_lshl_add_u64 v[80:81], v[150:151], 1, v[80:81]
	v_pk_mul_f32 v[74:75], v[84:85], v[74:75]
	v_pk_mul_f32 v[72:73], v[148:149], v[72:73]
	v_pk_mul_f32 v[70:71], v[84:85], v[70:71]
	v_pk_mul_f32 v[68:69], v[148:149], v[68:69]
	v_pk_mul_f32 v[66:67], v[84:85], v[66:67]
	s_and_b64 vcc, exec, s[10:11]
	v_pk_mul_f32 v[64:65], v[148:149], v[64:65]
	v_pk_mul_f32 v[78:79], v[84:85], v[78:79]
	v_pk_mul_f32 v[76:77], v[148:149], v[76:77]
	v_cvt_pk_bf16_f32 v72, v72, v73
	v_cvt_pk_bf16_f32 v73, v74, v75
	s_nop 0
	v_cvt_pk_bf16_f32 v74, v76, v77
	v_cvt_pk_bf16_f32 v75, v78, v79
	global_store_dwordx4 v[80:81], v[72:75], off
	s_cbranch_vccnz .LBB0_200
	s_nop 0
	v_lshlrev_b32_e32 v72, 4, v82
	v_and_or_b32 v72, v72, s96, v156
	v_lshlrev_b32_e32 v86, 2, v72
	global_load_dwordx4 v[72:75], v86, s[46:47]
	global_load_dwordx4 v[76:79], v86, s[46:47] offset:16
	global_load_dwordx4 v[82:85], v86, s[44:45]
	s_nop 0
	global_load_dwordx4 v[86:89], v86, s[44:45] offset:16
	v_and_b32_e32 v91, 64, v161
	v_xor_b32_e32 v90, 32, v161
	v_add_u32_e32 v91, 64, v91
	v_cmp_lt_i32_e32 vcc, v90, v91
	s_nop 1
	v_cndmask_b32_e32 v90, v161, v90, vcc
	v_lshlrev_b32_e32 v95, 2, v90
	ds_bpermute_b32 v90, v95, v68
	ds_bpermute_b32 v91, v95, v69
	ds_bpermute_b32 v92, v95, v70
	ds_bpermute_b32 v93, v95, v71
	ds_bpermute_b32 v94, v95, v64
	ds_bpermute_b32 v96, v95, v66
	ds_bpermute_b32 v97, v95, v67
	ds_bpermute_b32 v95, v95, v65
	s_waitcnt vmcnt(0) lgkmcnt(0)
	v_pk_mul_f32 v[74:75], v[74:75], v[92:93]
	v_pk_mul_f32 v[72:73], v[72:73], v[90:91]
	v_pk_mul_f32 v[78:79], v[78:79], v[96:97]
	v_pk_mul_f32 v[76:77], v[76:77], v[94:95]
	v_pk_mul_f32 v[72:73], v[136:137], v[72:73]
	v_pk_mul_f32 v[74:75], v[138:139], v[74:75]
	v_pk_mul_f32 v[76:77], v[136:137], v[76:77]
	v_pk_mul_f32 v[78:79], v[138:139], v[78:79]
	v_pk_fma_f32 v[70:71], v[70:71], v[84:85], v[74:75]
	v_pk_fma_f32 v[68:69], v[68:69], v[82:83], v[72:73]
	v_pk_fma_f32 v[66:67], v[66:67], v[88:89], v[78:79]
	v_pk_fma_f32 v[64:65], v[64:65], v[86:87], v[76:77]
.LBB0_200:
	v_cvt_pk_bf16_f32 v68, v68, v69
	v_cvt_pk_bf16_f32 v69, v70, v71
	s_nop 0
	v_cvt_pk_bf16_f32 v70, v64, v65
	v_cvt_pk_bf16_f32 v71, v66, v67
	global_store_dwordx4 v[80:81], v[68:71], off offset:256
	s_and_b64 vcc, exec, s[12:13]
	v_add_u32_e32 v66, 0x80, v163
	s_cbranch_vccnz .LBB0_204
	v_mul_f32_e32 v64, v57, v57
	v_mul_f32_e32 v65, v59, v59
	v_fmac_f32_e32 v64, v56, v56
	v_fmac_f32_e32 v65, v58, v58
	v_add_f32_e32 v64, v64, v65
	v_mul_f32_e32 v65, v53, v53
	v_mul_f32_e32 v67, v55, v55
	v_fmac_f32_e32 v65, v52, v52
	v_fmac_f32_e32 v67, v54, v54
	v_add_f32_e32 v65, v65, v67
	v_mul_f32_e32 v67, v61, v61
	v_mul_f32_e32 v68, v63, v63
	v_fmac_f32_e32 v67, v60, v60
	v_fmac_f32_e32 v68, v62, v62
	v_add_f32_e32 v67, v67, v68
	v_add_f32_e32 v64, v67, v64
	v_mul_f32_e32 v67, v49, v49
	v_mul_f32_e32 v68, v51, v51
	v_fmac_f32_e32 v67, v48, v48
	v_fmac_f32_e32 v68, v50, v50
	v_add_f32_e32 v67, v67, v68
	v_add_f32_e32 v65, v67, v65
	v_add_f32_e32 v65, v65, v64
	v_and_b32_e32 v67, 64, v161
	v_cndmask_b32_e64 v64, v64, v65, s[8:9]
	v_xor_b32_e32 v65, 16, v161
	v_add_u32_e32 v67, 64, v67
	v_cmp_lt_i32_e32 vcc, v65, v67
	s_nop 1
	v_cndmask_b32_e32 v65, v161, v65, vcc
	v_lshlrev_b32_e32 v65, 2, v65
	ds_bpermute_b32 v65, v65, v64
	s_waitcnt lgkmcnt(0)
	v_add_f32_e32 v64, v64, v65
	v_xor_b32_e32 v65, 32, v161
	v_cmp_lt_i32_e32 vcc, v65, v67
	s_nop 1
	v_cndmask_b32_e32 v65, v161, v65, vcc
	v_lshlrev_b32_e32 v65, 2, v65
	ds_bpermute_b32 v65, v65, v64
	s_and_saveexec_b64 s[74:75], s[0:1]
	s_cbranch_execz .LBB0_203
	s_and_b64 s[98:99], s[8:9], exec
	s_cselect_b32 s98, s43, s41
	s_cselect_b32 s99, s42, s40
	v_lshl_or_b32 v70, v66, 2, s86
	v_mov_b32_e32 v68, s99
	v_mov_b32_e32 v69, s98
	v_ashrrev_i32_e32 v71, 31, v70
	v_lshl_add_u64 v[68:69], v[70:71], 2, v[68:69]
	s_waitcnt lgkmcnt(0)
	v_add_f32_e32 v64, v64, v65
	global_store_dword v[68:69], v64, off

.LBB0_204:
	s_waitcnt lgkmcnt(0)
	v_mov_b64_e32 v[64:65], s[16:17]
	v_mad_i64_i32 v[64:65], s[74:75], v66, s92, v[64:65]
	v_mov_b32_e32 v68, v148
	v_mov_b32_e32 v69, v148
	v_lshl_add_u64 v[64:65], v[150:151], 1, v[64:65]
	v_pk_mul_f32 v[58:59], v[68:69], v[58:59]
	v_pk_mul_f32 v[56:57], v[148:149], v[56:57]
	v_pk_mul_f32 v[54:55], v[68:69], v[54:55]
	v_pk_mul_f32 v[52:53], v[148:149], v[52:53]
	v_pk_mul_f32 v[50:51], v[68:69], v[50:51]
	s_and_b64 vcc, exec, s[10:11]
	v_pk_mul_f32 v[48:49], v[148:149], v[48:49]
	v_pk_mul_f32 v[62:63], v[68:69], v[62:63]
	v_pk_mul_f32 v[60:61], v[148:149], v[60:61]
	v_cvt_pk_bf16_f32 v56, v56, v57
	v_cvt_pk_bf16_f32 v57, v58, v59
	s_nop 0
	v_cvt_pk_bf16_f32 v58, v60, v61
	v_cvt_pk_bf16_f32 v59, v62, v63
	global_store_dwordx4 v[64:65], v[56:59], off
	s_cbranch_vccnz .LBB0_206
	s_nop 0
	v_lshlrev_b32_e32 v56, 4, v66
	v_and_or_b32 v56, v56, s93, v156
	v_lshlrev_b32_e32 v70, 2, v56
	global_load_dwordx4 v[56:59], v70, s[46:47]
	global_load_dwordx4 v[60:63], v70, s[46:47] offset:16
	global_load_dwordx4 v[66:69], v70, s[44:45]
	s_nop 0
	global_load_dwordx4 v[70:73], v70, s[44:45] offset:16
	v_and_b32_e32 v75, 64, v161
	v_xor_b32_e32 v74, 32, v161
	v_add_u32_e32 v75, 64, v75
	v_cmp_lt_i32_e32 vcc, v74, v75
	s_nop 1
	v_cndmask_b32_e32 v74, v161, v74, vcc
	v_lshlrev_b32_e32 v79, 2, v74
	ds_bpermute_b32 v74, v79, v52
	ds_bpermute_b32 v75, v79, v53
	ds_bpermute_b32 v76, v79, v54
	ds_bpermute_b32 v77, v79, v55
	ds_bpermute_b32 v78, v79, v48
	ds_bpermute_b32 v80, v79, v50
	ds_bpermute_b32 v81, v79, v51
	ds_bpermute_b32 v79, v79, v49
	s_waitcnt vmcnt(0) lgkmcnt(0)
	v_pk_mul_f32 v[58:59], v[58:59], v[76:77]
	v_pk_mul_f32 v[56:57], v[56:57], v[74:75]
	v_pk_mul_f32 v[62:63], v[62:63], v[80:81]
	v_pk_mul_f32 v[60:61], v[60:61], v[78:79]
	v_pk_mul_f32 v[56:57], v[136:137], v[56:57]
	v_pk_mul_f32 v[58:59], v[138:139], v[58:59]
	v_pk_mul_f32 v[60:61], v[136:137], v[60:61]
	v_pk_mul_f32 v[62:63], v[138:139], v[62:63]
	v_pk_fma_f32 v[54:55], v[54:55], v[68:69], v[58:59]
	v_pk_fma_f32 v[52:53], v[52:53], v[66:67], v[56:57]
	v_pk_fma_f32 v[50:51], v[50:51], v[72:73], v[62:63]
	v_pk_fma_f32 v[48:49], v[48:49], v[70:71], v[60:61]
.LBB0_206:
	v_cvt_pk_bf16_f32 v52, v52, v53
	v_cvt_pk_bf16_f32 v53, v54, v55
	s_nop 0
	v_cvt_pk_bf16_f32 v54, v48, v49
	v_cvt_pk_bf16_f32 v55, v50, v51
	global_store_dwordx4 v[64:65], v[52:55], off offset:256
	s_and_b64 vcc, exec, s[12:13]
	v_add_u32_e32 v50, 0x90, v163
	s_cbranch_vccnz .LBB0_210
	v_mul_f32_e32 v48, v41, v41
	v_mul_f32_e32 v49, v43, v43
	v_fmac_f32_e32 v48, v40, v40
	v_fmac_f32_e32 v49, v42, v42
	v_add_f32_e32 v48, v48, v49
	v_mul_f32_e32 v49, v37, v37
	v_mul_f32_e32 v51, v39, v39
	v_fmac_f32_e32 v49, v36, v36
	v_fmac_f32_e32 v51, v38, v38
	v_add_f32_e32 v49, v49, v51
	v_mul_f32_e32 v51, v45, v45
	v_mul_f32_e32 v52, v47, v47
	v_fmac_f32_e32 v51, v44, v44
	v_fmac_f32_e32 v52, v46, v46
	v_add_f32_e32 v51, v51, v52
	v_add_f32_e32 v48, v51, v48
	v_mul_f32_e32 v51, v33, v33
	v_mul_f32_e32 v52, v35, v35
	v_fmac_f32_e32 v51, v32, v32
	v_fmac_f32_e32 v52, v34, v34
	v_add_f32_e32 v51, v51, v52
	v_add_f32_e32 v49, v51, v49
	v_add_f32_e32 v49, v49, v48
	v_and_b32_e32 v51, 64, v161
	v_cndmask_b32_e64 v48, v48, v49, s[8:9]
	v_xor_b32_e32 v49, 16, v161
	v_add_u32_e32 v51, 64, v51
	v_cmp_lt_i32_e32 vcc, v49, v51
	s_nop 1
	v_cndmask_b32_e32 v49, v161, v49, vcc
	v_lshlrev_b32_e32 v49, 2, v49
	ds_bpermute_b32 v49, v49, v48
	s_waitcnt lgkmcnt(0)
	v_add_f32_e32 v48, v48, v49
	v_xor_b32_e32 v49, 32, v161
	v_cmp_lt_i32_e32 vcc, v49, v51
	s_nop 1
	v_cndmask_b32_e32 v49, v161, v49, vcc
	v_lshlrev_b32_e32 v49, 2, v49
	ds_bpermute_b32 v49, v49, v48
	s_and_saveexec_b64 s[74:75], s[0:1]
	s_cbranch_execz .LBB0_209
	s_and_b64 s[98:99], s[8:9], exec
	s_cselect_b32 s98, s43, s41
	s_cselect_b32 s99, s42, s40
	v_lshl_or_b32 v54, v50, 2, s86
	v_mov_b32_e32 v52, s99
	v_mov_b32_e32 v53, s98
	v_ashrrev_i32_e32 v55, 31, v54
	v_lshl_add_u64 v[52:53], v[54:55], 2, v[52:53]
	s_waitcnt lgkmcnt(0)
	v_add_f32_e32 v48, v48, v49
	global_store_dword v[52:53], v48, off

.LBB0_210:
	s_waitcnt lgkmcnt(0)
	v_mov_b64_e32 v[48:49], s[16:17]
	v_mad_i64_i32 v[48:49], s[74:75], v50, s92, v[48:49]
	v_mov_b32_e32 v52, v148
	v_mov_b32_e32 v53, v148
	v_lshl_add_u64 v[48:49], v[150:151], 1, v[48:49]
	v_pk_mul_f32 v[42:43], v[52:53], v[42:43]
	v_pk_mul_f32 v[40:41], v[148:149], v[40:41]
	v_pk_mul_f32 v[38:39], v[52:53], v[38:39]
	v_pk_mul_f32 v[36:37], v[148:149], v[36:37]
	v_pk_mul_f32 v[34:35], v[52:53], v[34:35]
	s_and_b64 vcc, exec, s[10:11]
	v_pk_mul_f32 v[32:33], v[148:149], v[32:33]
	v_pk_mul_f32 v[46:47], v[52:53], v[46:47]
	v_pk_mul_f32 v[44:45], v[148:149], v[44:45]
	v_cvt_pk_bf16_f32 v40, v40, v41
	v_cvt_pk_bf16_f32 v41, v42, v43
	s_nop 0
	v_cvt_pk_bf16_f32 v42, v44, v45
	v_cvt_pk_bf16_f32 v43, v46, v47
	global_store_dwordx4 v[48:49], v[40:43], off
	s_cbranch_vccnz .LBB0_212
	s_nop 0
	v_lshlrev_b32_e32 v40, 4, v50
	v_and_or_b32 v40, v40, s94, v156
	v_lshlrev_b32_e32 v54, 2, v40
	global_load_dwordx4 v[40:43], v54, s[46:47]
	global_load_dwordx4 v[44:47], v54, s[46:47] offset:16
	global_load_dwordx4 v[50:53], v54, s[44:45]
	s_nop 0
	global_load_dwordx4 v[54:57], v54, s[44:45] offset:16
	v_and_b32_e32 v59, 64, v161
	v_xor_b32_e32 v58, 32, v161
	v_add_u32_e32 v59, 64, v59
	v_cmp_lt_i32_e32 vcc, v58, v59
	s_nop 1
	v_cndmask_b32_e32 v58, v161, v58, vcc
	v_lshlrev_b32_e32 v63, 2, v58
	ds_bpermute_b32 v58, v63, v36
	ds_bpermute_b32 v59, v63, v37
	ds_bpermute_b32 v60, v63, v38
	ds_bpermute_b32 v61, v63, v39
	ds_bpermute_b32 v62, v63, v32
	ds_bpermute_b32 v64, v63, v34
	ds_bpermute_b32 v65, v63, v35
	ds_bpermute_b32 v63, v63, v33
	s_waitcnt vmcnt(0) lgkmcnt(0)
	v_pk_mul_f32 v[42:43], v[42:43], v[60:61]
	v_pk_mul_f32 v[40:41], v[40:41], v[58:59]
	v_pk_mul_f32 v[46:47], v[46:47], v[64:65]
	v_pk_mul_f32 v[44:45], v[44:45], v[62:63]
	v_pk_mul_f32 v[40:41], v[136:137], v[40:41]
	v_pk_mul_f32 v[42:43], v[138:139], v[42:43]
	v_pk_mul_f32 v[44:45], v[136:137], v[44:45]
	v_pk_mul_f32 v[46:47], v[138:139], v[46:47]
	v_pk_fma_f32 v[38:39], v[38:39], v[52:53], v[42:43]
	v_pk_fma_f32 v[36:37], v[36:37], v[50:51], v[40:41]
	v_pk_fma_f32 v[34:35], v[34:35], v[56:57], v[46:47]
	v_pk_fma_f32 v[32:33], v[32:33], v[54:55], v[44:45]
.LBB0_212:
	v_cvt_pk_bf16_f32 v36, v36, v37
	v_cvt_pk_bf16_f32 v37, v38, v39
	s_nop 0
	v_cvt_pk_bf16_f32 v38, v32, v33
	v_cvt_pk_bf16_f32 v39, v34, v35
	global_store_dwordx4 v[48:49], v[36:39], off offset:256
	s_and_b64 vcc, exec, s[12:13]
	v_add_u32_e32 v34, 0xa0, v163
	s_cbranch_vccnz .LBB0_216
	v_mul_f32_e32 v32, v25, v25
	v_mul_f32_e32 v33, v27, v27
	v_fmac_f32_e32 v32, v24, v24
	v_fmac_f32_e32 v33, v26, v26
	v_add_f32_e32 v32, v32, v33
	v_mul_f32_e32 v33, v21, v21
	v_mul_f32_e32 v35, v23, v23
	v_fmac_f32_e32 v33, v20, v20
	v_fmac_f32_e32 v35, v22, v22
	v_add_f32_e32 v33, v33, v35
	v_mul_f32_e32 v35, v29, v29
	v_mul_f32_e32 v36, v31, v31
	v_fmac_f32_e32 v35, v28, v28
	v_fmac_f32_e32 v36, v30, v30
	v_add_f32_e32 v35, v35, v36
	v_add_f32_e32 v32, v35, v32
	v_mul_f32_e32 v35, v17, v17
	v_mul_f32_e32 v36, v19, v19
	v_fmac_f32_e32 v35, v16, v16
	v_fmac_f32_e32 v36, v18, v18
	v_add_f32_e32 v35, v35, v36
	v_add_f32_e32 v33, v35, v33
	v_add_f32_e32 v33, v33, v32
	v_and_b32_e32 v35, 64, v161
	v_cndmask_b32_e64 v32, v32, v33, s[8:9]
	v_xor_b32_e32 v33, 16, v161
	v_add_u32_e32 v35, 64, v35
	v_cmp_lt_i32_e32 vcc, v33, v35
	s_nop 1
	v_cndmask_b32_e32 v33, v161, v33, vcc
	v_lshlrev_b32_e32 v33, 2, v33
	ds_bpermute_b32 v33, v33, v32
	s_waitcnt lgkmcnt(0)
	v_add_f32_e32 v32, v32, v33
	v_xor_b32_e32 v33, 32, v161
	v_cmp_lt_i32_e32 vcc, v33, v35
	s_nop 1
	v_cndmask_b32_e32 v33, v161, v33, vcc
	v_lshlrev_b32_e32 v33, 2, v33
	ds_bpermute_b32 v33, v33, v32
	s_and_saveexec_b64 s[74:75], s[0:1]
	s_cbranch_execz .LBB0_215
	s_and_b64 s[98:99], s[8:9], exec
	s_cselect_b32 s98, s43, s41
	s_cselect_b32 s99, s42, s40
	v_lshl_or_b32 v38, v34, 2, s86
	v_mov_b32_e32 v36, s99
	v_mov_b32_e32 v37, s98
	v_ashrrev_i32_e32 v39, 31, v38
	v_lshl_add_u64 v[36:37], v[38:39], 2, v[36:37]
	s_waitcnt lgkmcnt(0)
	v_add_f32_e32 v32, v32, v33
	global_store_dword v[36:37], v32, off

.LBB0_216:
	s_waitcnt lgkmcnt(0)
	v_mov_b64_e32 v[32:33], s[16:17]
	v_mad_i64_i32 v[32:33], s[74:75], v34, s92, v[32:33]
	v_mov_b32_e32 v36, v148
	v_mov_b32_e32 v37, v148
	v_lshl_add_u64 v[32:33], v[150:151], 1, v[32:33]
	v_pk_mul_f32 v[26:27], v[36:37], v[26:27]
	v_pk_mul_f32 v[24:25], v[148:149], v[24:25]
	v_pk_mul_f32 v[22:23], v[36:37], v[22:23]
	v_pk_mul_f32 v[20:21], v[148:149], v[20:21]
	v_pk_mul_f32 v[18:19], v[36:37], v[18:19]
	s_and_b64 vcc, exec, s[10:11]
	v_pk_mul_f32 v[16:17], v[148:149], v[16:17]
	v_pk_mul_f32 v[30:31], v[36:37], v[30:31]
	v_pk_mul_f32 v[28:29], v[148:149], v[28:29]
	v_cvt_pk_bf16_f32 v24, v24, v25
	v_cvt_pk_bf16_f32 v25, v26, v27
	s_nop 0
	v_cvt_pk_bf16_f32 v26, v28, v29
	v_cvt_pk_bf16_f32 v27, v30, v31
	global_store_dwordx4 v[32:33], v[24:27], off
	s_cbranch_vccnz .LBB0_218
	s_nop 0
	v_lshlrev_b32_e32 v24, 4, v34
	v_and_or_b32 v24, v24, s95, v156
	v_lshlrev_b32_e32 v38, 2, v24
	global_load_dwordx4 v[24:27], v38, s[46:47]
	global_load_dwordx4 v[28:31], v38, s[46:47] offset:16
	global_load_dwordx4 v[34:37], v38, s[44:45]
	s_nop 0
	global_load_dwordx4 v[38:41], v38, s[44:45] offset:16
	v_and_b32_e32 v43, 64, v161
	v_xor_b32_e32 v42, 32, v161
	v_add_u32_e32 v43, 64, v43
	v_cmp_lt_i32_e32 vcc, v42, v43
	s_nop 1
	v_cndmask_b32_e32 v42, v161, v42, vcc
	v_lshlrev_b32_e32 v47, 2, v42
	ds_bpermute_b32 v42, v47, v20
	ds_bpermute_b32 v43, v47, v21
	ds_bpermute_b32 v44, v47, v22
	ds_bpermute_b32 v45, v47, v23
	ds_bpermute_b32 v46, v47, v16
	ds_bpermute_b32 v48, v47, v18
	ds_bpermute_b32 v49, v47, v19
	ds_bpermute_b32 v47, v47, v17
	s_waitcnt vmcnt(0) lgkmcnt(0)
	v_pk_mul_f32 v[26:27], v[26:27], v[44:45]
	v_pk_mul_f32 v[24:25], v[24:25], v[42:43]
	v_pk_mul_f32 v[30:31], v[30:31], v[48:49]
	v_pk_mul_f32 v[28:29], v[28:29], v[46:47]
	v_pk_mul_f32 v[24:25], v[136:137], v[24:25]
	v_pk_mul_f32 v[26:27], v[138:139], v[26:27]
	v_pk_mul_f32 v[28:29], v[136:137], v[28:29]
	v_pk_mul_f32 v[30:31], v[138:139], v[30:31]
	v_pk_fma_f32 v[22:23], v[22:23], v[36:37], v[26:27]
	v_pk_fma_f32 v[20:21], v[20:21], v[34:35], v[24:25]
	v_pk_fma_f32 v[18:19], v[18:19], v[40:41], v[30:31]
	v_pk_fma_f32 v[16:17], v[16:17], v[38:39], v[28:29]
.LBB0_218:
	v_cvt_pk_bf16_f32 v20, v20, v21
	v_cvt_pk_bf16_f32 v21, v22, v23
	s_nop 0
	v_cvt_pk_bf16_f32 v22, v16, v17
	v_cvt_pk_bf16_f32 v23, v18, v19
	global_store_dwordx4 v[32:33], v[20:23], off offset:256
	s_and_b64 vcc, exec, s[12:13]
	v_add_u32_e32 v18, 0xb0, v163
	s_cbranch_vccnz .LBB0_222
	v_mul_f32_e32 v16, v9, v9
	v_mul_f32_e32 v17, v11, v11
	v_fmac_f32_e32 v16, v8, v8
	v_fmac_f32_e32 v17, v10, v10
	v_add_f32_e32 v16, v16, v17
	v_mul_f32_e32 v17, v5, v5
	v_mul_f32_e32 v19, v7, v7
	v_fmac_f32_e32 v17, v4, v4
	v_fmac_f32_e32 v19, v6, v6
	v_add_f32_e32 v17, v17, v19
	v_mul_f32_e32 v19, v13, v13
	v_mul_f32_e32 v20, v15, v15
	v_fmac_f32_e32 v19, v12, v12
	v_fmac_f32_e32 v20, v14, v14
	v_add_f32_e32 v19, v19, v20
	v_add_f32_e32 v16, v19, v16
	v_mul_f32_e32 v19, v1, v1
	v_mul_f32_e32 v20, v3, v3
	v_fmac_f32_e32 v19, v0, v0
	v_fmac_f32_e32 v20, v2, v2
	v_add_f32_e32 v19, v19, v20
	v_add_f32_e32 v17, v19, v17
	v_add_f32_e32 v17, v17, v16
	v_and_b32_e32 v19, 64, v161
	v_cndmask_b32_e64 v16, v16, v17, s[8:9]
	v_xor_b32_e32 v17, 16, v161
	v_add_u32_e32 v19, 64, v19
	v_cmp_lt_i32_e32 vcc, v17, v19
	s_nop 1
	v_cndmask_b32_e32 v17, v161, v17, vcc
	v_lshlrev_b32_e32 v17, 2, v17
	ds_bpermute_b32 v17, v17, v16
	s_waitcnt lgkmcnt(0)
	v_add_f32_e32 v16, v16, v17
	v_xor_b32_e32 v17, 32, v161
	v_cmp_lt_i32_e32 vcc, v17, v19
	s_nop 1
	v_cndmask_b32_e32 v17, v161, v17, vcc
	v_lshlrev_b32_e32 v17, 2, v17
	ds_bpermute_b32 v17, v17, v16
	s_and_saveexec_b64 s[12:13], s[0:1]
	s_cbranch_execz .LBB0_221
	s_and_b64 s[8:9], s[8:9], exec
	s_cselect_b32 s8, s43, s41
	s_cselect_b32 s9, s42, s40
	v_lshl_or_b32 v22, v18, 2, s86
	v_mov_b32_e32 v20, s9
	v_mov_b32_e32 v21, s8
	v_ashrrev_i32_e32 v23, 31, v22
	v_lshl_add_u64 v[20:21], v[22:23], 2, v[20:21]
	s_waitcnt lgkmcnt(0)
	v_add_f32_e32 v16, v16, v17
	global_store_dword v[20:21], v16, off

.LBB0_222:
	s_waitcnt lgkmcnt(0)
	v_mov_b64_e32 v[16:17], s[16:17]
	v_mad_i64_i32 v[16:17], s[8:9], v18, s92, v[16:17]
	v_mov_b32_e32 v20, v148
	v_mov_b32_e32 v21, v148
	v_lshl_add_u64 v[16:17], v[150:151], 1, v[16:17]
	v_pk_mul_f32 v[10:11], v[20:21], v[10:11]
	v_pk_mul_f32 v[8:9], v[148:149], v[8:9]
	v_pk_mul_f32 v[6:7], v[20:21], v[6:7]
	v_pk_mul_f32 v[4:5], v[148:149], v[4:5]
	v_pk_mul_f32 v[2:3], v[20:21], v[2:3]
	s_and_b64 vcc, exec, s[10:11]
	v_pk_mul_f32 v[0:1], v[148:149], v[0:1]
	v_pk_mul_f32 v[14:15], v[20:21], v[14:15]
	v_pk_mul_f32 v[12:13], v[148:149], v[12:13]
	v_cvt_pk_bf16_f32 v8, v8, v9
	v_cvt_pk_bf16_f32 v9, v10, v11
	s_nop 0
	v_cvt_pk_bf16_f32 v10, v12, v13
	v_cvt_pk_bf16_f32 v11, v14, v15
	global_store_dwordx4 v[16:17], v[8:11], off
	s_cbranch_vccnz .LBB0_224
	s_nop 0
	v_lshlrev_b32_e32 v8, 4, v18
	v_and_or_b32 v8, v8, s96, v156
	v_lshlrev_b32_e32 v22, 2, v8
	global_load_dwordx4 v[8:11], v22, s[46:47]
	global_load_dwordx4 v[12:15], v22, s[46:47] offset:16
	global_load_dwordx4 v[18:21], v22, s[44:45]
	s_nop 0
	global_load_dwordx4 v[22:25], v22, s[44:45] offset:16
	v_and_b32_e32 v27, 64, v161
	v_xor_b32_e32 v26, 32, v161
	v_add_u32_e32 v27, 64, v27
	v_cmp_lt_i32_e32 vcc, v26, v27
	s_nop 1
	v_cndmask_b32_e32 v26, v161, v26, vcc
	v_lshlrev_b32_e32 v31, 2, v26
	ds_bpermute_b32 v26, v31, v4
	ds_bpermute_b32 v27, v31, v5
	ds_bpermute_b32 v28, v31, v6
	ds_bpermute_b32 v29, v31, v7
	ds_bpermute_b32 v30, v31, v0
	ds_bpermute_b32 v32, v31, v2
	ds_bpermute_b32 v33, v31, v3
	ds_bpermute_b32 v31, v31, v1
	s_waitcnt vmcnt(0) lgkmcnt(0)
	v_pk_mul_f32 v[10:11], v[10:11], v[28:29]
	v_pk_mul_f32 v[8:9], v[8:9], v[26:27]
	v_pk_mul_f32 v[14:15], v[14:15], v[32:33]
	v_pk_mul_f32 v[12:13], v[12:13], v[30:31]
	v_pk_mul_f32 v[8:9], v[136:137], v[8:9]
	v_pk_mul_f32 v[10:11], v[138:139], v[10:11]
	v_pk_mul_f32 v[12:13], v[136:137], v[12:13]
	v_pk_mul_f32 v[14:15], v[138:139], v[14:15]
	v_pk_fma_f32 v[6:7], v[6:7], v[20:21], v[10:11]
	v_pk_fma_f32 v[4:5], v[4:5], v[18:19], v[8:9]
	v_pk_fma_f32 v[2:3], v[2:3], v[24:25], v[14:15]
	v_pk_fma_f32 v[0:1], v[0:1], v[22:23], v[12:13]
.LBB0_224:
	v_cvt_pk_bf16_f32 v4, v4, v5
	v_cvt_pk_bf16_f32 v5, v6, v7
	s_nop 0
	v_cvt_pk_bf16_f32 v6, v0, v1
	v_cvt_pk_bf16_f32 v7, v2, v3
	global_store_dwordx4 v[16:17], v[4:7], off offset:256
	s_and_b64 vcc, exec, s[6:7]
	s_mov_b64 s[6:7], -1
	s_cbranch_vccnz .LBB0_164
	s_andn2_b64 vcc, exec, s[62:63]
	s_cbranch_vccnz .LBB0_163
	s_barrier
	s_branch .LBB0_163
